# v193 + static priority raise for the younger wave half (waves 4-7) during the attention phase
# baseline (speedup 1.0000x reference)
.LBB0_1112:
	s_cmp_lt_i32 s28, 11
	s_cselect_b64 s[2:3], -1, 0
	s_and_b64 s[2:3], s[2:3], s[0:1]
	s_andn2_b64 vcc, exec, s[2:3]
	s_cbranch_vccnz .LBB0_1140
	s_cmpk_gt_i32 s76, 0x3ff
	s_cbranch_scc1 .LBB0_1139
	s_add_u32 s72, s24, 0x1e200000
	s_addc_u32 s73, s25, 0
	s_add_u32 s74, s24, 0x20200000
	s_addc_u32 s75, s25, 0
	s_add_u32 s4, s24, 0x16a00000
	s_addc_u32 s5, s25, 0
	s_add_u32 s8, s24, 0x22200000
	s_addc_u32 s9, s25, 0
	s_lshr_b32 s11, s77, 7
	s_lshr_b32 s1, s77, 5
	s_bfe_u32 s0, s77, 0x10006
	s_and_b32 s26, s1, 12
	s_lshl_b32 s1, s11, 15
	s_lshl_b32 s11, s11, 12
	s_add_i32 s79, s11, 0
	s_lshl_b32 s11, s0, 10
	v_readlane_b32 s59, v250, 2
	s_lshr_b32 s7, s77, 8
	s_cmp_eq_u32 s7, 1
	s_cbranch_scc0 .Latt_prio_lo
	s_setprio 2
